# speedup vs baseline: 1.0220x; 1.0012x over previous
; __device__ __forceinline__ void scan_phase(const ScanArgs& s, char* shm) {
;     ...
;         if (c >= 1 && c <= NCH) {
;           const int q = c - 1;
;           const float4* sr = (const float4*)(shm + OFF_SRING + (q & 1) * (TC * 2048) + sw * 1024 + lane * 16);
;           const float* rv = (const float*)(shm + OFF_RRING + (q & 3) * (TC * 256)) + j * 4;
;           float* yb = (float*)(shm + OFF_YBUF + (q & 1) * (TC * 32));
; #pragma unroll
;           for (int u = 0; u < TC / 2; ++u) {
;             const int t = 2 * u + tp;
;             const float4 S = sr[t * 128];
;             const float4 r4 = *(const float4*)(rv + t * 64);
;             float d = (S.x * r4.x + S.y * r4.y) + (S.z * r4.z + S.w * r4.w);
;             d = row16_allreduce(d);
;             yb[t * 8 + row] = d;
;           }
.LBB0_166:
	s_andn2_b64 vcc, exec, s[68:69]
	s_cbranch_vccnz .LBB0_156
	s_add_i32 s68, s79, -1
	s_and_b32 s68, s68, 1
	s_and_b32 s69, s64, 0x3000
	v_lshl_add_u32 v10, s68, 15, v171
	v_add_u32_e32 v11, s69, v173
	v_lshl_add_u32 v12, s68, 9, v174
	v_readfirstlane_b32 s68, v177
	s_cmp_lg_u32 s68, 0
	s_cbranch_scc1 .Lyw_b
	ds_read_b128 v[16:19], v10 offset:0
	ds_read_b128 v[20:23], v11 offset:0
	ds_read_b128 v[24:27], v10 offset:2048
	ds_read_b128 v[28:31], v11 offset:256
	s_waitcnt lgkmcnt(2)
	v_mul_f32_e32 v17, v17, v21
	v_fmac_f32_e32 v17, v16, v20
	v_mul_f32_e32 v16, v19, v23
	v_fmac_f32_e32 v16, v18, v22
	v_add_f32_e32 v16, v17, v16
	ds_read_b128 v[32:35], v10 offset:4096
	ds_read_b128 v[36:39], v11 offset:512
	s_waitcnt lgkmcnt(2)
	v_add_f32_dpp v16, v16, v16 quad_perm:[1,0,3,2] row_mask:0xf bank_mask:0xf bound_ctrl:1
	v_mul_f32_e32 v25, v25, v29
	v_fmac_f32_e32 v25, v24, v28
	v_add_f32_dpp v16, v16, v16 quad_perm:[2,3,0,1] row_mask:0xf bank_mask:0xf bound_ctrl:1
	v_mul_f32_e32 v24, v27, v31
	v_fmac_f32_e32 v24, v26, v30
	v_add_f32_dpp v16, v16, v16 row_half_mirror row_mask:0xf bank_mask:0xf bound_ctrl:1
	v_add_f32_e32 v24, v25, v24
	s_nop 0
	v_add_f32_dpp v16, v16, v16 row_mirror row_mask:0xf bank_mask:0xf bound_ctrl:1
	ds_write_b32 v12, v16 offset:0
	ds_read_b128 v[16:19], v10 offset:6144
	ds_read_b128 v[20:23], v11 offset:768
	s_waitcnt lgkmcnt(3)
	v_add_f32_dpp v24, v24, v24 quad_perm:[1,0,3,2] row_mask:0xf bank_mask:0xf bound_ctrl:1
	v_mul_f32_e32 v33, v33, v37
	v_fmac_f32_e32 v33, v32, v36
	v_add_f32_dpp v24, v24, v24 quad_perm:[2,3,0,1] row_mask:0xf bank_mask:0xf bound_ctrl:1
	v_mul_f32_e32 v32, v35, v39
	v_fmac_f32_e32 v32, v34, v38
	v_add_f32_dpp v24, v24, v24 row_half_mirror row_mask:0xf bank_mask:0xf bound_ctrl:1
	v_add_f32_e32 v32, v33, v32
	s_nop 0
	v_add_f32_dpp v24, v24, v24 row_mirror row_mask:0xf bank_mask:0xf bound_ctrl:1
	ds_write_b32 v12, v24 offset:32
	ds_read_b128 v[24:27], v10 offset:8192
	ds_read_b128 v[28:31], v11 offset:1024
	s_waitcnt lgkmcnt(3)
	v_add_f32_dpp v32, v32, v32 quad_perm:[1,0,3,2] row_mask:0xf bank_mask:0xf bound_ctrl:1
	v_mul_f32_e32 v17, v17, v21
	v_fmac_f32_e32 v17, v16, v20
	v_add_f32_dpp v32, v32, v32 quad_perm:[2,3,0,1] row_mask:0xf bank_mask:0xf bound_ctrl:1
	v_mul_f32_e32 v16, v19, v23
	v_fmac_f32_e32 v16, v18, v22
	v_add_f32_dpp v32, v32, v32 row_half_mirror row_mask:0xf bank_mask:0xf bound_ctrl:1
	v_add_f32_e32 v16, v17, v16
	s_nop 0
	v_add_f32_dpp v32, v32, v32 row_mirror row_mask:0xf bank_mask:0xf bound_ctrl:1
	ds_write_b32 v12, v32 offset:64
	ds_read_b128 v[32:35], v10 offset:10240
	ds_read_b128 v[36:39], v11 offset:1280
	s_waitcnt lgkmcnt(3)
	v_add_f32_dpp v16, v16, v16 quad_perm:[1,0,3,2] row_mask:0xf bank_mask:0xf bound_ctrl:1
	v_mul_f32_e32 v25, v25, v29
	v_fmac_f32_e32 v25, v24, v28
	v_add_f32_dpp v16, v16, v16 quad_perm:[2,3,0,1] row_mask:0xf bank_mask:0xf bound_ctrl:1
	v_mul_f32_e32 v24, v27, v31
	v_fmac_f32_e32 v24, v26, v30
	v_add_f32_dpp v16, v16, v16 row_half_mirror row_mask:0xf bank_mask:0xf bound_ctrl:1
	v_add_f32_e32 v24, v25, v24
	s_nop 0
	v_add_f32_dpp v16, v16, v16 row_mirror row_mask:0xf bank_mask:0xf bound_ctrl:1
	ds_write_b32 v12, v16 offset:96
	s_waitcnt lgkmcnt(1)
	v_add_f32_dpp v24, v24, v24 quad_perm:[1,0,3,2] row_mask:0xf bank_mask:0xf bound_ctrl:1
	v_mul_f32_e32 v33, v33, v37
	v_fmac_f32_e32 v33, v32, v36
	v_add_f32_dpp v24, v24, v24 quad_perm:[2,3,0,1] row_mask:0xf bank_mask:0xf bound_ctrl:1
	v_mul_f32_e32 v32, v35, v39
	v_fmac_f32_e32 v32, v34, v38
	v_add_f32_dpp v24, v24, v24 row_half_mirror row_mask:0xf bank_mask:0xf bound_ctrl:1
	v_add_f32_e32 v32, v33, v32
	s_nop 0
	v_add_f32_dpp v24, v24, v24 row_mirror row_mask:0xf bank_mask:0xf bound_ctrl:1
	ds_write_b32 v12, v24 offset:128
	v_add_f32_dpp v32, v32, v32 quad_perm:[1,0,3,2] row_mask:0xf bank_mask:0xf bound_ctrl:1
	s_nop 1
	v_add_f32_dpp v32, v32, v32 quad_perm:[2,3,0,1] row_mask:0xf bank_mask:0xf bound_ctrl:1
	s_nop 1
	v_add_f32_dpp v32, v32, v32 row_half_mirror row_mask:0xf bank_mask:0xf bound_ctrl:1
	s_nop 1
	v_add_f32_dpp v32, v32, v32 row_mirror row_mask:0xf bank_mask:0xf bound_ctrl:1
	ds_write_b32 v12, v32 offset:160
	s_branch .LBB0_156
; __device__ __forceinline__ void scan_phase(const ScanArgs& s, char* shm) {
;     ...
; #pragma unroll
;           for (int u = 0; u < TC / 2; ++u) {
;             const int t = 2 * u + tp;
;             const float4 S = sr[t * 128];
;             const float4 r4 = *(const float4*)(rv + t * 64);
;             float d = (S.x * r4.x + S.y * r4.y) + (S.z * r4.z + S.w * r4.w);
;             d = row16_allreduce(d);
;             yb[t * 8 + row] = d;
;           }
.Lyw_b:
	ds_read_b128 v[16:19], v10 offset:12288
	ds_read_b128 v[20:23], v11 offset:1536
	ds_read_b128 v[24:27], v10 offset:14336
	ds_read_b128 v[28:31], v11 offset:1792
	s_waitcnt lgkmcnt(2)
	v_mul_f32_e32 v17, v17, v21
	v_fmac_f32_e32 v17, v16, v20
	v_mul_f32_e32 v16, v19, v23
	v_fmac_f32_e32 v16, v18, v22
	v_add_f32_e32 v16, v17, v16
	ds_read_b128 v[32:35], v10 offset:16384
	ds_read_b128 v[36:39], v11 offset:2048
	s_waitcnt lgkmcnt(2)
	v_add_f32_dpp v16, v16, v16 quad_perm:[1,0,3,2] row_mask:0xf bank_mask:0xf bound_ctrl:1
	v_mul_f32_e32 v25, v25, v29
	v_fmac_f32_e32 v25, v24, v28
	v_add_f32_dpp v16, v16, v16 quad_perm:[2,3,0,1] row_mask:0xf bank_mask:0xf bound_ctrl:1
	v_mul_f32_e32 v24, v27, v31
	v_fmac_f32_e32 v24, v26, v30
	v_add_f32_dpp v16, v16, v16 row_half_mirror row_mask:0xf bank_mask:0xf bound_ctrl:1
	v_add_f32_e32 v24, v25, v24
	s_nop 0
	v_add_f32_dpp v16, v16, v16 row_mirror row_mask:0xf bank_mask:0xf bound_ctrl:1
	ds_write_b32 v12, v16 offset:192
	ds_read_b128 v[16:19], v10 offset:18432
	ds_read_b128 v[20:23], v11 offset:2304
	s_waitcnt lgkmcnt(3)
	v_add_f32_dpp v24, v24, v24 quad_perm:[1,0,3,2] row_mask:0xf bank_mask:0xf bound_ctrl:1
	v_mul_f32_e32 v33, v33, v37
	v_fmac_f32_e32 v33, v32, v36
	v_add_f32_dpp v24, v24, v24 quad_perm:[2,3,0,1] row_mask:0xf bank_mask:0xf bound_ctrl:1
	v_mul_f32_e32 v32, v35, v39
	v_fmac_f32_e32 v32, v34, v38
	v_add_f32_dpp v24, v24, v24 row_half_mirror row_mask:0xf bank_mask:0xf bound_ctrl:1
	v_add_f32_e32 v32, v33, v32
	s_nop 0
	v_add_f32_dpp v24, v24, v24 row_mirror row_mask:0xf bank_mask:0xf bound_ctrl:1
	ds_write_b32 v12, v24 offset:224
	ds_read_b128 v[24:27], v10 offset:20480
	ds_read_b128 v[28:31], v11 offset:2560
	s_waitcnt lgkmcnt(3)
	v_add_f32_dpp v32, v32, v32 quad_perm:[1,0,3,2] row_mask:0xf bank_mask:0xf bound_ctrl:1
	v_mul_f32_e32 v17, v17, v21
	v_fmac_f32_e32 v17, v16, v20
	v_add_f32_dpp v32, v32, v32 quad_perm:[2,3,0,1] row_mask:0xf bank_mask:0xf bound_ctrl:1
	v_mul_f32_e32 v16, v19, v23
	v_fmac_f32_e32 v16, v18, v22
	v_add_f32_dpp v32, v32, v32 row_half_mirror row_mask:0xf bank_mask:0xf bound_ctrl:1
	v_add_f32_e32 v16, v17, v16
	s_nop 0
	v_add_f32_dpp v32, v32, v32 row_mirror row_mask:0xf bank_mask:0xf bound_ctrl:1
	ds_write_b32 v12, v32 offset:256
	ds_read_b128 v[32:35], v10 offset:22528
	ds_read_b128 v[36:39], v11 offset:2816
	s_waitcnt lgkmcnt(3)
	v_add_f32_dpp v16, v16, v16 quad_perm:[1,0,3,2] row_mask:0xf bank_mask:0xf bound_ctrl:1
	v_mul_f32_e32 v25, v25, v29
	v_fmac_f32_e32 v25, v24, v28
	v_add_f32_dpp v16, v16, v16 quad_perm:[2,3,0,1] row_mask:0xf bank_mask:0xf bound_ctrl:1
	v_mul_f32_e32 v24, v27, v31
	v_fmac_f32_e32 v24, v26, v30
	v_add_f32_dpp v16, v16, v16 row_half_mirror row_mask:0xf bank_mask:0xf bound_ctrl:1
	v_add_f32_e32 v24, v25, v24
	s_nop 0
	v_add_f32_dpp v16, v16, v16 row_mirror row_mask:0xf bank_mask:0xf bound_ctrl:1
	ds_write_b32 v12, v16 offset:288
	ds_read_b128 v[16:19], v10 offset:24576
	ds_read_b128 v[20:23], v11 offset:3072
	s_waitcnt lgkmcnt(3)
	v_add_f32_dpp v24, v24, v24 quad_perm:[1,0,3,2] row_mask:0xf bank_mask:0xf bound_ctrl:1
	v_mul_f32_e32 v33, v33, v37
	v_fmac_f32_e32 v33, v32, v36
	v_add_f32_dpp v24, v24, v24 quad_perm:[2,3,0,1] row_mask:0xf bank_mask:0xf bound_ctrl:1
	v_mul_f32_e32 v32, v35, v39
	v_fmac_f32_e32 v32, v34, v38
	v_add_f32_dpp v24, v24, v24 row_half_mirror row_mask:0xf bank_mask:0xf bound_ctrl:1
	v_add_f32_e32 v32, v33, v32
	s_nop 0
	v_add_f32_dpp v24, v24, v24 row_mirror row_mask:0xf bank_mask:0xf bound_ctrl:1
	ds_write_b32 v12, v24 offset:320
	ds_read_b128 v[24:27], v10 offset:26624
	ds_read_b128 v[28:31], v11 offset:3328
	s_waitcnt lgkmcnt(3)
	v_add_f32_dpp v32, v32, v32 quad_perm:[1,0,3,2] row_mask:0xf bank_mask:0xf bound_ctrl:1
	v_mul_f32_e32 v17, v17, v21
	v_fmac_f32_e32 v17, v16, v20
	v_add_f32_dpp v32, v32, v32 quad_perm:[2,3,0,1] row_mask:0xf bank_mask:0xf bound_ctrl:1
	v_mul_f32_e32 v16, v19, v23
	v_fmac_f32_e32 v16, v18, v22
	v_add_f32_dpp v32, v32, v32 row_half_mirror row_mask:0xf bank_mask:0xf bound_ctrl:1
	v_add_f32_e32 v16, v17, v16
	s_nop 0
	v_add_f32_dpp v32, v32, v32 row_mirror row_mask:0xf bank_mask:0xf bound_ctrl:1
	ds_write_b32 v12, v32 offset:352
	ds_read_b128 v[32:35], v10 offset:28672
	ds_read_b128 v[36:39], v11 offset:3584
	s_waitcnt lgkmcnt(3)
	v_add_f32_dpp v16, v16, v16 quad_perm:[1,0,3,2] row_mask:0xf bank_mask:0xf bound_ctrl:1
	v_mul_f32_e32 v25, v25, v29
	v_fmac_f32_e32 v25, v24, v28
	v_add_f32_dpp v16, v16, v16 quad_perm:[2,3,0,1] row_mask:0xf bank_mask:0xf bound_ctrl:1
	v_mul_f32_e32 v24, v27, v31
	v_fmac_f32_e32 v24, v26, v30
	v_add_f32_dpp v16, v16, v16 row_half_mirror row_mask:0xf bank_mask:0xf bound_ctrl:1
	v_add_f32_e32 v24, v25, v24
	s_nop 0
	v_add_f32_dpp v16, v16, v16 row_mirror row_mask:0xf bank_mask:0xf bound_ctrl:1
	ds_write_b32 v12, v16 offset:384
	ds_read_b128 v[16:19], v10 offset:30720
	ds_read_b128 v[20:23], v11 offset:3840
	s_waitcnt lgkmcnt(3)
	v_add_f32_dpp v24, v24, v24 quad_perm:[1,0,3,2] row_mask:0xf bank_mask:0xf bound_ctrl:1
	v_mul_f32_e32 v33, v33, v37
	v_fmac_f32_e32 v33, v32, v36
	v_add_f32_dpp v24, v24, v24 quad_perm:[2,3,0,1] row_mask:0xf bank_mask:0xf bound_ctrl:1
	v_mul_f32_e32 v32, v35, v39
	v_fmac_f32_e32 v32, v34, v38
	v_add_f32_dpp v24, v24, v24 row_half_mirror row_mask:0xf bank_mask:0xf bound_ctrl:1
	v_add_f32_e32 v32, v33, v32
	s_nop 0
	v_add_f32_dpp v24, v24, v24 row_mirror row_mask:0xf bank_mask:0xf bound_ctrl:1
	ds_write_b32 v12, v24 offset:416
	s_waitcnt lgkmcnt(1)
	v_add_f32_dpp v32, v32, v32 quad_perm:[1,0,3,2] row_mask:0xf bank_mask:0xf bound_ctrl:1
	v_mul_f32_e32 v17, v17, v21
	v_fmac_f32_e32 v17, v16, v20
	v_add_f32_dpp v32, v32, v32 quad_perm:[2,3,0,1] row_mask:0xf bank_mask:0xf bound_ctrl:1
	v_mul_f32_e32 v16, v19, v23
	v_fmac_f32_e32 v16, v18, v22
	v_add_f32_dpp v32, v32, v32 row_half_mirror row_mask:0xf bank_mask:0xf bound_ctrl:1
	v_add_f32_e32 v16, v17, v16
	s_nop 0
	v_add_f32_dpp v32, v32, v32 row_mirror row_mask:0xf bank_mask:0xf bound_ctrl:1
	ds_write_b32 v12, v32 offset:448
	v_add_f32_dpp v16, v16, v16 quad_perm:[1,0,3,2] row_mask:0xf bank_mask:0xf bound_ctrl:1
	s_nop 1
	v_add_f32_dpp v16, v16, v16 quad_perm:[2,3,0,1] row_mask:0xf bank_mask:0xf bound_ctrl:1
	s_nop 1
	v_add_f32_dpp v16, v16, v16 row_half_mirror row_mask:0xf bank_mask:0xf bound_ctrl:1
	s_nop 1
	v_add_f32_dpp v16, v16, v16 row_mirror row_mask:0xf bank_mask:0xf bound_ctrl:1
	ds_write_b32 v12, v16 offset:480
	s_branch .LBB0_156
